# NA item rewritten by hand: QK loads 20 deep, 64 rpb bias loads batched branch-free, softmax + PV with 8 V loads in flight; on top of mLSTM LDS pipelining / bank-conflict fix / DPP gate scan
# speedup vs baseline: 1.0017x; 1.0017x over previous
; __device__ __forceinline__ unsigned pk2(float lo, float hi) { unsigned r; asm("v_cvt_pk_bf16_f32 %0, %1, %2" : "=v"(r) : "v"(lo), "v"(hi)); return r; }
; __device__ void na_phase(const bf16_t* zna  , const bf16_t* vtn  , const float* rpb, bf16_t* ya, int half, unsigned* counter) {
;     ...
;         mx = fmaxf(mx, __shfl_xor(mx, 16)); mx = fmaxf(mx, __shfl_xor(mx, 32));
;         float sm = 0.f;
; #pragma unroll
;         for (int t = 0; t < 16; ++t)
; #pragma unroll
;             for (int j = 0; j < 4; ++j) { const float e = __expf(s[t][j] - mx); s[t][j] = e; sm += e; }
;         sm += __shfl_xor(sm, 16); sm += __shfl_xor(sm, 32);
;         f32x4 o[8];
; #pragma unroll
;         for (int dt = 0; dt < 8; ++dt) o[dt] = (f32x4){0.f, 0.f, 0.f, 0.f};
;         const bf16_t* vb = vtn + (size_t)(h * 128 + fr) * TH + (size_t)krow0 * 64 + kstart + fq * 8;
; #pragma unroll
;         for (int a = 0; a < 8; ++a) {
;             const u32x4 pw = (u32x4){pk2(s[2 * a][0], s[2 * a][1]), pk2(s[2 * a][2], s[2 * a][3]), pk2(s[2 * a + 1][0], s[2 * a + 1][1]), pk2(s[2 * a + 1][2], s[2 * a + 1][3])};
;             const bf16x8 pf = *(const bf16x8*)&pw;
; #pragma unroll
;             for (int dt = 0; dt < 8; ++dt) { const bf16x8 vf = *(const bf16x8*)(vb + (size_t)dt * 16 * TH + a * 64);
;                 o[dt] = __builtin_amdgcn_mfma_f32_16x16x32_bf16(vf, pf, o[dt], 0, 0, 0); }
;         }
.LBB0_179:
	s_or_b64 exec, exec, s[12:13]
	s_lshl_b32 s8, s1, 7
	v_or_b32_e32 v114, s8, v84
	s_lshl_b32 s52, s8, 1
	s_mov_b32 s9, 0x14000
	v_mov_b64_e32 v[162:163], s[96:97]
	v_mad_u64_u32 v[162:163], s[10:11], v114, s9, v[162:163]
	s_mov_b32 s1, s53
	s_lshl_b64 s[0:1], s[0:1], 7
	v_lshl_add_u64 v[162:163], v[162:163], 0, s[0:1]
	v_lshlrev_b32_e32 v184, 1, v79
	v_lshl_add_u64 v[162:163], v[162:163], 0, v[184:185]
	v_lshlrev_b32_e32 v184, 1, v76
	v_lshl_add_u64 v[162:163], v[162:163], 0, v[184:185]
	v_mov_b32_e32 v79, v185
	v_add_co_u32_e32 v164, vcc, 0x140000, v162
	s_nop 1
	v_addc_co_u32_e32 v165, vcc, 0, v163, vcc
	v_add_co_u32_e32 v166, vcc, 0x280000, v162
	s_nop 1
	v_addc_co_u32_e32 v167, vcc, 0, v163, vcc
	v_add_co_u32_e32 v168, vcc, 0x3c0000, v162
	s_nop 1
	v_addc_co_u32_e32 v169, vcc, 0, v163, vcc
	v_add_co_u32_e32 v170, vcc, 0x500000, v162
	s_nop 1
	v_addc_co_u32_e32 v171, vcc, 0, v163, vcc
	v_add_co_u32_e32 v172, vcc, 0x640000, v162
	s_nop 1
	v_addc_co_u32_e32 v173, vcc, 0, v163, vcc
	v_add_co_u32_e32 v174, vcc, 0x780000, v162
	s_nop 1
	v_addc_co_u32_e32 v175, vcc, 0, v163, vcc
	v_add_co_u32_e32 v176, vcc, 0x8c0000, v162
	s_nop 1
	v_addc_co_u32_e32 v177, vcc, 0, v163, vcc
	global_load_dwordx4 v[204:207], v[162:163], off
	global_load_dwordx4 v[208:211], v[164:165], off
	global_load_dwordx4 v[212:215], v[166:167], off
	global_load_dwordx4 v[216:219], v[168:169], off
	global_load_dwordx4 v[220:223], v[170:171], off
	global_load_dwordx4 v[224:227], v[172:173], off
	global_load_dwordx4 v[228:231], v[174:175], off
	global_load_dwordx4 v[178:181], v[176:177], off
	v_xor_b32_e32 v110, 16, v240
	v_lshlrev_b32_e32 v110, 2, v110
	v_xor_b32_e32 v111, 32, v240
	v_lshlrev_b32_e32 v111, 2, v111
	v_max_f32_e32 v112, v57, v56
	v_max3_f32 v112, v112, v41, v40
	v_max3_f32 v112, v112, v43, v42
	v_max3_f32 v112, v112, v29, v28
	v_max3_f32 v112, v112, v31, v30
	v_max3_f32 v112, v112, v21, v20
	v_max3_f32 v112, v112, v23, v22
	v_max3_f32 v112, v112, v17, v16
	v_max3_f32 v112, v112, v19, v18
	v_max3_f32 v112, v112, v64, v12
	v_max3_f32 v112, v112, v15, v14
	v_max3_f32 v112, v112, v83, v82
	v_max3_f32 v112, v112, v75, v74
	v_max3_f32 v112, v112, v87, v86
	v_max3_f32 v112, v112, v89, v88
	v_max3_f32 v112, v112, v91, v90
	v_max3_f32 v112, v112, v93, v92
	v_max3_f32 v112, v112, v49, v48
	v_max3_f32 v112, v112, v95, v94
	v_max3_f32 v112, v112, v97, v96
	v_max3_f32 v112, v112, v99, v98
	v_max3_f32 v112, v112, v36, v37
	v_max3_f32 v112, v112, v38, v39
	v_max3_f32 v112, v112, v33, v32
	v_max3_f32 v112, v112, v101, v100
	v_max3_f32 v112, v112, v103, v102
	v_max3_f32 v112, v112, v26, v27
	v_max3_f32 v112, v112, v105, v104
	v_max3_f32 v112, v112, v11, v10
	v_max3_f32 v112, v112, v107, v106
	v_max3_f32 v112, v112, v109, v108
	v_max3_f32 v112, v112, v1, v0
	ds_bpermute_b32 v114, v110, v112
	s_waitcnt lgkmcnt(0)
	v_max_f32_e32 v114, v114, v114
	v_max_f32_e32 v112, v112, v114
	ds_bpermute_b32 v114, v111, v112
	s_waitcnt lgkmcnt(0)
	v_max_f32_e32 v114, v114, v114
	v_max_f32_e32 v112, v112, v114
	v_sub_f32_e32 v57, v57, v112
	v_sub_f32_e32 v56, v56, v112
	v_sub_f32_e32 v41, v41, v112
	v_sub_f32_e32 v40, v40, v112
	v_sub_f32_e32 v43, v43, v112
	v_sub_f32_e32 v42, v42, v112
	v_sub_f32_e32 v29, v29, v112
	v_sub_f32_e32 v28, v28, v112
	v_mul_f32_e32 v57, 0x3fb8aa3b, v57
	v_mul_f32_e32 v56, 0x3fb8aa3b, v56
	v_mul_f32_e32 v41, 0x3fb8aa3b, v41
	v_mul_f32_e32 v40, 0x3fb8aa3b, v40
	v_mul_f32_e32 v43, 0x3fb8aa3b, v43
	v_mul_f32_e32 v42, 0x3fb8aa3b, v42
	v_mul_f32_e32 v29, 0x3fb8aa3b, v29
	v_mul_f32_e32 v28, 0x3fb8aa3b, v28
	v_exp_f32_e32 v57, v57
	v_exp_f32_e32 v56, v56
	v_exp_f32_e32 v41, v41
	v_exp_f32_e32 v40, v40
	v_exp_f32_e32 v43, v43
	v_exp_f32_e32 v42, v42
	v_exp_f32_e32 v29, v29
	v_exp_f32_e32 v28, v28
	v_add_f32_e32 v113, 0, v57
	v_add_f32_e32 v113, v56, v113
	v_add_f32_e32 v113, v41, v113
	v_add_f32_e32 v113, v40, v113
	v_add_f32_e32 v113, v43, v113
	v_add_f32_e32 v113, v42, v113
	v_add_f32_e32 v113, v29, v113
	v_add_f32_e32 v113, v28, v113
	v_cvt_pk_bf16_f32 v154, v57, v56
	v_cvt_pk_bf16_f32 v155, v41, v40
	v_cvt_pk_bf16_f32 v156, v43, v42
	v_cvt_pk_bf16_f32 v157, v29, v28
	s_nop 1
	s_waitcnt vmcnt(7)
	v_mfma_f32_16x16x32_bf16 v[122:125], v[204:207], v[154:157], 0
	global_load_dwordx4 v[204:207], v[162:163], off offset:128
	s_waitcnt vmcnt(7)
	v_mfma_f32_16x16x32_bf16 v[126:129], v[208:211], v[154:157], 0
	global_load_dwordx4 v[208:211], v[164:165], off offset:128
	s_waitcnt vmcnt(7)
	v_mfma_f32_16x16x32_bf16 v[130:133], v[212:215], v[154:157], 0
	global_load_dwordx4 v[212:215], v[166:167], off offset:128
	s_waitcnt vmcnt(7)
	v_mfma_f32_16x16x32_bf16 v[134:137], v[216:219], v[154:157], 0
	global_load_dwordx4 v[216:219], v[168:169], off offset:128
	s_waitcnt vmcnt(7)
	v_mfma_f32_16x16x32_bf16 v[138:141], v[220:223], v[154:157], 0
	global_load_dwordx4 v[220:223], v[170:171], off offset:128
	s_waitcnt vmcnt(7)
	v_mfma_f32_16x16x32_bf16 v[142:145], v[224:227], v[154:157], 0
	global_load_dwordx4 v[224:227], v[172:173], off offset:128
	s_waitcnt vmcnt(7)
	v_mfma_f32_16x16x32_bf16 v[146:149], v[228:231], v[154:157], 0
	global_load_dwordx4 v[228:231], v[174:175], off offset:128
	s_waitcnt vmcnt(7)
; __device__ __forceinline__ unsigned pk2(float lo, float hi) { unsigned r; asm("v_cvt_pk_bf16_f32 %0, %1, %2" : "=v"(r) : "v"(lo), "v"(hi)); return r; }
; __device__ void na_phase(const bf16_t* zna  , const bf16_t* vtn  , const float* rpb, bf16_t* ya, int half, unsigned* counter) {
;     ...
;         for (int t = 0; t < 16; ++t)
; #pragma unroll
;             for (int j = 0; j < 4; ++j) { const float e = __expf(s[t][j] - mx); s[t][j] = e; sm += e; }
;         sm += __shfl_xor(sm, 16); sm += __shfl_xor(sm, 32);
;         f32x4 o[8];
; #pragma unroll
;         for (int dt = 0; dt < 8; ++dt) o[dt] = (f32x4){0.f, 0.f, 0.f, 0.f};
;         const bf16_t* vb = vtn + (size_t)(h * 128 + fr) * TH + (size_t)krow0 * 64 + kstart + fq * 8;
; #pragma unroll
;         for (int a = 0; a < 8; ++a) {
;             const u32x4 pw = (u32x4){pk2(s[2 * a][0], s[2 * a][1]), pk2(s[2 * a][2], s[2 * a][3]), pk2(s[2 * a + 1][0], s[2 * a + 1][1]), pk2(s[2 * a + 1][2], s[2 * a + 1][3])};
;             const bf16x8 pf = *(const bf16x8*)&pw;
; #pragma unroll
;             for (int dt = 0; dt < 8; ++dt) { const bf16x8 vf = *(const bf16x8*)(vb + (size_t)dt * 16 * TH + a * 64);
;                 o[dt] = __builtin_amdgcn_mfma_f32_16x16x32_bf16(vf, pf, o[dt], 0, 0, 0); }
;         }
	v_mfma_f32_16x16x32_bf16 v[150:153], v[178:181], v[154:157], 0
	global_load_dwordx4 v[178:181], v[176:177], off offset:128
	v_sub_f32_e32 v31, v31, v112
	v_sub_f32_e32 v30, v30, v112
	v_sub_f32_e32 v21, v21, v112
	v_sub_f32_e32 v20, v20, v112
	v_sub_f32_e32 v23, v23, v112
	v_sub_f32_e32 v22, v22, v112
	v_sub_f32_e32 v17, v17, v112
	v_sub_f32_e32 v16, v16, v112
	v_mul_f32_e32 v31, 0x3fb8aa3b, v31
	v_mul_f32_e32 v30, 0x3fb8aa3b, v30
	v_mul_f32_e32 v21, 0x3fb8aa3b, v21
	v_mul_f32_e32 v20, 0x3fb8aa3b, v20
	v_mul_f32_e32 v23, 0x3fb8aa3b, v23
	v_mul_f32_e32 v22, 0x3fb8aa3b, v22
	v_mul_f32_e32 v17, 0x3fb8aa3b, v17
	v_mul_f32_e32 v16, 0x3fb8aa3b, v16
	v_exp_f32_e32 v31, v31
	v_exp_f32_e32 v30, v30
	v_exp_f32_e32 v21, v21
	v_exp_f32_e32 v20, v20
	v_exp_f32_e32 v23, v23
	v_exp_f32_e32 v22, v22
	v_exp_f32_e32 v17, v17
	v_exp_f32_e32 v16, v16
	v_add_f32_e32 v113, v31, v113
	v_add_f32_e32 v113, v30, v113
	v_add_f32_e32 v113, v21, v113
	v_add_f32_e32 v113, v20, v113
	v_add_f32_e32 v113, v23, v113
	v_add_f32_e32 v113, v22, v113
	v_add_f32_e32 v113, v17, v113
	v_add_f32_e32 v113, v16, v113
	v_cvt_pk_bf16_f32 v158, v31, v30
	v_cvt_pk_bf16_f32 v159, v21, v20
	v_cvt_pk_bf16_f32 v160, v23, v22
	v_cvt_pk_bf16_f32 v161, v17, v16
	s_nop 1
	s_waitcnt vmcnt(7)
	v_mfma_f32_16x16x32_bf16 v[122:125], v[204:207], v[158:161], v[122:125]
	global_load_dwordx4 v[204:207], v[162:163], off offset:256
	s_waitcnt vmcnt(7)
	v_mfma_f32_16x16x32_bf16 v[126:129], v[208:211], v[158:161], v[126:129]
	global_load_dwordx4 v[208:211], v[164:165], off offset:256
	s_waitcnt vmcnt(7)
	v_mfma_f32_16x16x32_bf16 v[130:133], v[212:215], v[158:161], v[130:133]
	global_load_dwordx4 v[212:215], v[166:167], off offset:256
	s_waitcnt vmcnt(7)
	v_mfma_f32_16x16x32_bf16 v[134:137], v[216:219], v[158:161], v[134:137]
	global_load_dwordx4 v[216:219], v[168:169], off offset:256
	s_waitcnt vmcnt(7)
	v_mfma_f32_16x16x32_bf16 v[138:141], v[220:223], v[158:161], v[138:141]
	global_load_dwordx4 v[220:223], v[170:171], off offset:256
	s_waitcnt vmcnt(7)
	v_mfma_f32_16x16x32_bf16 v[142:145], v[224:227], v[158:161], v[142:145]
	global_load_dwordx4 v[224:227], v[172:173], off offset:256
	s_waitcnt vmcnt(7)
	v_mfma_f32_16x16x32_bf16 v[146:149], v[228:231], v[158:161], v[146:149]
	global_load_dwordx4 v[228:231], v[174:175], off offset:256
	s_waitcnt vmcnt(7)
	v_mfma_f32_16x16x32_bf16 v[150:153], v[178:181], v[158:161], v[150:153]
	global_load_dwordx4 v[178:181], v[176:177], off offset:256
	v_sub_f32_e32 v19, v19, v112
	v_sub_f32_e32 v18, v18, v112
	v_sub_f32_e32 v64, v64, v112
	v_sub_f32_e32 v12, v12, v112
	v_sub_f32_e32 v15, v15, v112
	v_sub_f32_e32 v14, v14, v112
	v_sub_f32_e32 v83, v83, v112
	v_sub_f32_e32 v82, v82, v112
	v_mul_f32_e32 v19, 0x3fb8aa3b, v19
	v_mul_f32_e32 v18, 0x3fb8aa3b, v18
	v_mul_f32_e32 v64, 0x3fb8aa3b, v64
	v_mul_f32_e32 v12, 0x3fb8aa3b, v12
	v_mul_f32_e32 v15, 0x3fb8aa3b, v15
	v_mul_f32_e32 v14, 0x3fb8aa3b, v14
	v_mul_f32_e32 v83, 0x3fb8aa3b, v83
	v_mul_f32_e32 v82, 0x3fb8aa3b, v82
	v_exp_f32_e32 v19, v19
	v_exp_f32_e32 v18, v18
	v_exp_f32_e32 v64, v64
	v_exp_f32_e32 v12, v12
	v_exp_f32_e32 v15, v15
	v_exp_f32_e32 v14, v14
	v_exp_f32_e32 v83, v83
	v_exp_f32_e32 v82, v82
	v_add_f32_e32 v113, v19, v113
	v_add_f32_e32 v113, v18, v113
	v_add_f32_e32 v113, v64, v113
	v_add_f32_e32 v113, v12, v113
	v_add_f32_e32 v113, v15, v113
	v_add_f32_e32 v113, v14, v113
	v_add_f32_e32 v113, v83, v113
	v_add_f32_e32 v113, v82, v113
	v_cvt_pk_bf16_f32 v154, v19, v18
	v_cvt_pk_bf16_f32 v155, v64, v12
	v_cvt_pk_bf16_f32 v156, v15, v14
	v_cvt_pk_bf16_f32 v157, v83, v82
	s_nop 1
	s_waitcnt vmcnt(7)
	v_mfma_f32_16x16x32_bf16 v[122:125], v[204:207], v[154:157], v[122:125]
	global_load_dwordx4 v[204:207], v[162:163], off offset:384
	s_waitcnt vmcnt(7)
	v_mfma_f32_16x16x32_bf16 v[126:129], v[208:211], v[154:157], v[126:129]
	global_load_dwordx4 v[208:211], v[164:165], off offset:384
	s_waitcnt vmcnt(7)
	v_mfma_f32_16x16x32_bf16 v[130:133], v[212:215], v[154:157], v[130:133]
	global_load_dwordx4 v[212:215], v[166:167], off offset:384
	s_waitcnt vmcnt(7)
	v_mfma_f32_16x16x32_bf16 v[134:137], v[216:219], v[154:157], v[134:137]
	global_load_dwordx4 v[216:219], v[168:169], off offset:384
	s_waitcnt vmcnt(7)
	v_mfma_f32_16x16x32_bf16 v[138:141], v[220:223], v[154:157], v[138:141]
	global_load_dwordx4 v[220:223], v[170:171], off offset:384
	s_waitcnt vmcnt(7)
	v_mfma_f32_16x16x32_bf16 v[142:145], v[224:227], v[154:157], v[142:145]
	global_load_dwordx4 v[224:227], v[172:173], off offset:384
	s_waitcnt vmcnt(7)
	v_mfma_f32_16x16x32_bf16 v[146:149], v[228:231], v[154:157], v[146:149]
	global_load_dwordx4 v[228:231], v[174:175], off offset:384
	s_waitcnt vmcnt(7)
	v_mfma_f32_16x16x32_bf16 v[150:153], v[178:181], v[154:157], v[150:153]
	global_load_dwordx4 v[178:181], v[176:177], off offset:384
	v_sub_f32_e32 v75, v75, v112
	v_sub_f32_e32 v74, v74, v112
	v_sub_f32_e32 v87, v87, v112
	v_sub_f32_e32 v86, v86, v112
	v_sub_f32_e32 v89, v89, v112
	v_sub_f32_e32 v88, v88, v112
	v_sub_f32_e32 v91, v91, v112
	v_sub_f32_e32 v90, v90, v112
	v_mul_f32_e32 v75, 0x3fb8aa3b, v75
	v_mul_f32_e32 v74, 0x3fb8aa3b, v74
	v_mul_f32_e32 v87, 0x3fb8aa3b, v87
	v_mul_f32_e32 v86, 0x3fb8aa3b, v86
	v_mul_f32_e32 v89, 0x3fb8aa3b, v89
	v_mul_f32_e32 v88, 0x3fb8aa3b, v88
	v_mul_f32_e32 v91, 0x3fb8aa3b, v91
	v_mul_f32_e32 v90, 0x3fb8aa3b, v90
	v_exp_f32_e32 v75, v75
	v_exp_f32_e32 v74, v74
	v_exp_f32_e32 v87, v87
	v_exp_f32_e32 v86, v86
	v_exp_f32_e32 v89, v89
	v_exp_f32_e32 v88, v88
	v_exp_f32_e32 v91, v91
	v_exp_f32_e32 v90, v90
	v_add_f32_e32 v113, v75, v113
	v_add_f32_e32 v113, v74, v113
	v_add_f32_e32 v113, v87, v113
	v_add_f32_e32 v113, v86, v113
	v_add_f32_e32 v113, v89, v113
	v_add_f32_e32 v113, v88, v113
	v_add_f32_e32 v113, v91, v113
	v_add_f32_e32 v113, v90, v113
	v_cvt_pk_bf16_f32 v158, v75, v74
	v_cvt_pk_bf16_f32 v159, v87, v86
	v_cvt_pk_bf16_f32 v160, v89, v88
	v_cvt_pk_bf16_f32 v161, v91, v90
	s_nop 1
	s_waitcnt vmcnt(7)
; __device__ __forceinline__ unsigned pk2(float lo, float hi) { unsigned r; asm("v_cvt_pk_bf16_f32 %0, %1, %2" : "=v"(r) : "v"(lo), "v"(hi)); return r; }
; __device__ void na_phase(const bf16_t* zna  , const bf16_t* vtn  , const float* rpb, bf16_t* ya, int half, unsigned* counter) {
;     ...
;         for (int t = 0; t < 16; ++t)
; #pragma unroll
;             for (int j = 0; j < 4; ++j) { const float e = __expf(s[t][j] - mx); s[t][j] = e; sm += e; }
;         sm += __shfl_xor(sm, 16); sm += __shfl_xor(sm, 32);
;         f32x4 o[8];
; #pragma unroll
;         for (int dt = 0; dt < 8; ++dt) o[dt] = (f32x4){0.f, 0.f, 0.f, 0.f};
;         const bf16_t* vb = vtn + (size_t)(h * 128 + fr) * TH + (size_t)krow0 * 64 + kstart + fq * 8;
; #pragma unroll
;         for (int a = 0; a < 8; ++a) {
;             const u32x4 pw = (u32x4){pk2(s[2 * a][0], s[2 * a][1]), pk2(s[2 * a][2], s[2 * a][3]), pk2(s[2 * a + 1][0], s[2 * a + 1][1]), pk2(s[2 * a + 1][2], s[2 * a + 1][3])};
;             const bf16x8 pf = *(const bf16x8*)&pw;
; #pragma unroll
;             for (int dt = 0; dt < 8; ++dt) { const bf16x8 vf = *(const bf16x8*)(vb + (size_t)dt * 16 * TH + a * 64);
;                 o[dt] = __builtin_amdgcn_mfma_f32_16x16x32_bf16(vf, pf, o[dt], 0, 0, 0); }
;         }
	v_mfma_f32_16x16x32_bf16 v[122:125], v[204:207], v[158:161], v[122:125]
	global_load_dwordx4 v[204:207], v[162:163], off offset:512
	s_waitcnt vmcnt(7)
	v_mfma_f32_16x16x32_bf16 v[126:129], v[208:211], v[158:161], v[126:129]
	global_load_dwordx4 v[208:211], v[164:165], off offset:512
	s_waitcnt vmcnt(7)
	v_mfma_f32_16x16x32_bf16 v[130:133], v[212:215], v[158:161], v[130:133]
	global_load_dwordx4 v[212:215], v[166:167], off offset:512
	s_waitcnt vmcnt(7)
	v_mfma_f32_16x16x32_bf16 v[134:137], v[216:219], v[158:161], v[134:137]
	global_load_dwordx4 v[216:219], v[168:169], off offset:512
	s_waitcnt vmcnt(7)
	v_mfma_f32_16x16x32_bf16 v[138:141], v[220:223], v[158:161], v[138:141]
	global_load_dwordx4 v[220:223], v[170:171], off offset:512
	s_waitcnt vmcnt(7)
	v_mfma_f32_16x16x32_bf16 v[142:145], v[224:227], v[158:161], v[142:145]
	global_load_dwordx4 v[224:227], v[172:173], off offset:512
	s_waitcnt vmcnt(7)
	v_mfma_f32_16x16x32_bf16 v[146:149], v[228:231], v[158:161], v[146:149]
	global_load_dwordx4 v[228:231], v[174:175], off offset:512
	s_waitcnt vmcnt(7)
	v_mfma_f32_16x16x32_bf16 v[150:153], v[178:181], v[158:161], v[150:153]
	global_load_dwordx4 v[178:181], v[176:177], off offset:512
	v_sub_f32_e32 v93, v93, v112
	v_sub_f32_e32 v92, v92, v112
	v_sub_f32_e32 v49, v49, v112
	v_sub_f32_e32 v48, v48, v112
	v_sub_f32_e32 v95, v95, v112
	v_sub_f32_e32 v94, v94, v112
	v_sub_f32_e32 v97, v97, v112
	v_sub_f32_e32 v96, v96, v112
	v_mul_f32_e32 v93, 0x3fb8aa3b, v93
	v_mul_f32_e32 v92, 0x3fb8aa3b, v92
	v_mul_f32_e32 v49, 0x3fb8aa3b, v49
	v_mul_f32_e32 v48, 0x3fb8aa3b, v48
	v_mul_f32_e32 v95, 0x3fb8aa3b, v95
	v_mul_f32_e32 v94, 0x3fb8aa3b, v94
	v_mul_f32_e32 v97, 0x3fb8aa3b, v97
	v_mul_f32_e32 v96, 0x3fb8aa3b, v96
	v_exp_f32_e32 v93, v93
	v_exp_f32_e32 v92, v92
	v_exp_f32_e32 v49, v49
	v_exp_f32_e32 v48, v48
	v_exp_f32_e32 v95, v95
	v_exp_f32_e32 v94, v94
	v_exp_f32_e32 v97, v97
	v_exp_f32_e32 v96, v96
	v_add_f32_e32 v113, v93, v113
	v_add_f32_e32 v113, v92, v113
	v_add_f32_e32 v113, v49, v113
	v_add_f32_e32 v113, v48, v113
	v_add_f32_e32 v113, v95, v113
	v_add_f32_e32 v113, v94, v113
	v_add_f32_e32 v113, v97, v113
	v_add_f32_e32 v113, v96, v113
	v_cvt_pk_bf16_f32 v154, v93, v92
	v_cvt_pk_bf16_f32 v155, v49, v48
	v_cvt_pk_bf16_f32 v156, v95, v94
	v_cvt_pk_bf16_f32 v157, v97, v96
	s_nop 1
	s_waitcnt vmcnt(7)
	v_mfma_f32_16x16x32_bf16 v[122:125], v[204:207], v[154:157], v[122:125]
	global_load_dwordx4 v[204:207], v[162:163], off offset:640
	s_waitcnt vmcnt(7)
	v_mfma_f32_16x16x32_bf16 v[126:129], v[208:211], v[154:157], v[126:129]
	global_load_dwordx4 v[208:211], v[164:165], off offset:640
	s_waitcnt vmcnt(7)
	v_mfma_f32_16x16x32_bf16 v[130:133], v[212:215], v[154:157], v[130:133]
	global_load_dwordx4 v[212:215], v[166:167], off offset:640
	s_waitcnt vmcnt(7)
	v_mfma_f32_16x16x32_bf16 v[134:137], v[216:219], v[154:157], v[134:137]
	global_load_dwordx4 v[216:219], v[168:169], off offset:640
	s_waitcnt vmcnt(7)
	v_mfma_f32_16x16x32_bf16 v[138:141], v[220:223], v[154:157], v[138:141]
	global_load_dwordx4 v[220:223], v[170:171], off offset:640
	s_waitcnt vmcnt(7)
	v_mfma_f32_16x16x32_bf16 v[142:145], v[224:227], v[154:157], v[142:145]
	global_load_dwordx4 v[224:227], v[172:173], off offset:640
	s_waitcnt vmcnt(7)
	v_mfma_f32_16x16x32_bf16 v[146:149], v[228:231], v[154:157], v[146:149]
	global_load_dwordx4 v[228:231], v[174:175], off offset:640
	s_waitcnt vmcnt(7)
	v_mfma_f32_16x16x32_bf16 v[150:153], v[178:181], v[154:157], v[150:153]
	global_load_dwordx4 v[178:181], v[176:177], off offset:640
	v_sub_f32_e32 v99, v99, v112
	v_sub_f32_e32 v98, v98, v112
	v_sub_f32_e32 v36, v36, v112
	v_sub_f32_e32 v37, v37, v112
	v_sub_f32_e32 v38, v38, v112
	v_sub_f32_e32 v39, v39, v112
	v_sub_f32_e32 v33, v33, v112
	v_sub_f32_e32 v32, v32, v112
	v_mul_f32_e32 v99, 0x3fb8aa3b, v99
	v_mul_f32_e32 v98, 0x3fb8aa3b, v98
	v_mul_f32_e32 v36, 0x3fb8aa3b, v36
	v_mul_f32_e32 v37, 0x3fb8aa3b, v37
	v_mul_f32_e32 v38, 0x3fb8aa3b, v38
	v_mul_f32_e32 v39, 0x3fb8aa3b, v39
	v_mul_f32_e32 v33, 0x3fb8aa3b, v33
	v_mul_f32_e32 v32, 0x3fb8aa3b, v32
	v_exp_f32_e32 v99, v99
	v_exp_f32_e32 v98, v98
	v_exp_f32_e32 v36, v36
	v_exp_f32_e32 v37, v37
	v_exp_f32_e32 v38, v38
	v_exp_f32_e32 v39, v39
	v_exp_f32_e32 v33, v33
	v_exp_f32_e32 v32, v32
	v_add_f32_e32 v113, v99, v113
	v_add_f32_e32 v113, v98, v113
	v_add_f32_e32 v113, v36, v113
	v_add_f32_e32 v113, v37, v113
	v_add_f32_e32 v113, v38, v113
	v_add_f32_e32 v113, v39, v113
	v_add_f32_e32 v113, v33, v113
	v_add_f32_e32 v113, v32, v113
	v_cvt_pk_bf16_f32 v158, v99, v98
	v_cvt_pk_bf16_f32 v159, v36, v37
	v_cvt_pk_bf16_f32 v160, v38, v39
	v_cvt_pk_bf16_f32 v161, v33, v32
	s_nop 1
	s_waitcnt vmcnt(7)
	v_mfma_f32_16x16x32_bf16 v[122:125], v[204:207], v[158:161], v[122:125]
	global_load_dwordx4 v[204:207], v[162:163], off offset:768
	s_waitcnt vmcnt(7)
	v_mfma_f32_16x16x32_bf16 v[126:129], v[208:211], v[158:161], v[126:129]
	global_load_dwordx4 v[208:211], v[164:165], off offset:768
	s_waitcnt vmcnt(7)
	v_mfma_f32_16x16x32_bf16 v[130:133], v[212:215], v[158:161], v[130:133]
	global_load_dwordx4 v[212:215], v[166:167], off offset:768
	s_waitcnt vmcnt(7)
	v_mfma_f32_16x16x32_bf16 v[134:137], v[216:219], v[158:161], v[134:137]
	global_load_dwordx4 v[216:219], v[168:169], off offset:768
	s_waitcnt vmcnt(7)
	v_mfma_f32_16x16x32_bf16 v[138:141], v[220:223], v[158:161], v[138:141]
	global_load_dwordx4 v[220:223], v[170:171], off offset:768
	s_waitcnt vmcnt(7)
	v_mfma_f32_16x16x32_bf16 v[142:145], v[224:227], v[158:161], v[142:145]
	global_load_dwordx4 v[224:227], v[172:173], off offset:768
	s_waitcnt vmcnt(7)
; __device__ __forceinline__ unsigned pk2(float lo, float hi) { unsigned r; asm("v_cvt_pk_bf16_f32 %0, %1, %2" : "=v"(r) : "v"(lo), "v"(hi)); return r; }
; __device__ void na_phase(const bf16_t* zna  , const bf16_t* vtn  , const float* rpb, bf16_t* ya, int half, unsigned* counter) {
;     ...
;         for (int t = 0; t < 16; ++t)
; #pragma unroll
;             for (int j = 0; j < 4; ++j) { const float e = __expf(s[t][j] - mx); s[t][j] = e; sm += e; }
;         sm += __shfl_xor(sm, 16); sm += __shfl_xor(sm, 32);
;         f32x4 o[8];
; #pragma unroll
;         for (int dt = 0; dt < 8; ++dt) o[dt] = (f32x4){0.f, 0.f, 0.f, 0.f};
;         const bf16_t* vb = vtn + (size_t)(h * 128 + fr) * TH + (size_t)krow0 * 64 + kstart + fq * 8;
; #pragma unroll
;         for (int a = 0; a < 8; ++a) {
;             const u32x4 pw = (u32x4){pk2(s[2 * a][0], s[2 * a][1]), pk2(s[2 * a][2], s[2 * a][3]), pk2(s[2 * a + 1][0], s[2 * a + 1][1]), pk2(s[2 * a + 1][2], s[2 * a + 1][3])};
;             const bf16x8 pf = *(const bf16x8*)&pw;
; #pragma unroll
;             for (int dt = 0; dt < 8; ++dt) { const bf16x8 vf = *(const bf16x8*)(vb + (size_t)dt * 16 * TH + a * 64);
;                 o[dt] = __builtin_amdgcn_mfma_f32_16x16x32_bf16(vf, pf, o[dt], 0, 0, 0); }
;         }
	v_mfma_f32_16x16x32_bf16 v[146:149], v[228:231], v[158:161], v[146:149]
	global_load_dwordx4 v[228:231], v[174:175], off offset:768
	s_waitcnt vmcnt(7)
	v_mfma_f32_16x16x32_bf16 v[150:153], v[178:181], v[158:161], v[150:153]
	global_load_dwordx4 v[178:181], v[176:177], off offset:768
	v_sub_f32_e32 v101, v101, v112
	v_sub_f32_e32 v100, v100, v112
	v_sub_f32_e32 v103, v103, v112
	v_sub_f32_e32 v102, v102, v112
	v_sub_f32_e32 v26, v26, v112
	v_sub_f32_e32 v27, v27, v112
	v_sub_f32_e32 v105, v105, v112
	v_sub_f32_e32 v104, v104, v112
	v_mul_f32_e32 v101, 0x3fb8aa3b, v101
	v_mul_f32_e32 v100, 0x3fb8aa3b, v100
	v_mul_f32_e32 v103, 0x3fb8aa3b, v103
	v_mul_f32_e32 v102, 0x3fb8aa3b, v102
	v_mul_f32_e32 v26, 0x3fb8aa3b, v26
	v_mul_f32_e32 v27, 0x3fb8aa3b, v27
	v_mul_f32_e32 v105, 0x3fb8aa3b, v105
	v_mul_f32_e32 v104, 0x3fb8aa3b, v104
	v_exp_f32_e32 v101, v101
	v_exp_f32_e32 v100, v100
	v_exp_f32_e32 v103, v103
	v_exp_f32_e32 v102, v102
	v_exp_f32_e32 v26, v26
	v_exp_f32_e32 v27, v27
	v_exp_f32_e32 v105, v105
	v_exp_f32_e32 v104, v104
	v_add_f32_e32 v113, v101, v113
	v_add_f32_e32 v113, v100, v113
	v_add_f32_e32 v113, v103, v113
	v_add_f32_e32 v113, v102, v113
	v_add_f32_e32 v113, v26, v113
	v_add_f32_e32 v113, v27, v113
	v_add_f32_e32 v113, v105, v113
	v_add_f32_e32 v113, v104, v113
	v_cvt_pk_bf16_f32 v154, v101, v100
	v_cvt_pk_bf16_f32 v155, v103, v102
	v_cvt_pk_bf16_f32 v156, v26, v27
	v_cvt_pk_bf16_f32 v157, v105, v104
	s_nop 1
	s_waitcnt vmcnt(7)
	v_mfma_f32_16x16x32_bf16 v[122:125], v[204:207], v[154:157], v[122:125]
	global_load_dwordx4 v[204:207], v[162:163], off offset:896
	s_waitcnt vmcnt(7)
	v_mfma_f32_16x16x32_bf16 v[126:129], v[208:211], v[154:157], v[126:129]
	global_load_dwordx4 v[208:211], v[164:165], off offset:896
	s_waitcnt vmcnt(7)
	v_mfma_f32_16x16x32_bf16 v[130:133], v[212:215], v[154:157], v[130:133]
	global_load_dwordx4 v[212:215], v[166:167], off offset:896
	s_waitcnt vmcnt(7)
	v_mfma_f32_16x16x32_bf16 v[134:137], v[216:219], v[154:157], v[134:137]
	global_load_dwordx4 v[216:219], v[168:169], off offset:896
	s_waitcnt vmcnt(7)
	v_mfma_f32_16x16x32_bf16 v[138:141], v[220:223], v[154:157], v[138:141]
	global_load_dwordx4 v[220:223], v[170:171], off offset:896
	s_waitcnt vmcnt(7)
	v_mfma_f32_16x16x32_bf16 v[142:145], v[224:227], v[154:157], v[142:145]
	global_load_dwordx4 v[224:227], v[172:173], off offset:896
	s_waitcnt vmcnt(7)
	v_mfma_f32_16x16x32_bf16 v[146:149], v[228:231], v[154:157], v[146:149]
	global_load_dwordx4 v[228:231], v[174:175], off offset:896
	s_waitcnt vmcnt(7)
	v_mfma_f32_16x16x32_bf16 v[150:153], v[178:181], v[154:157], v[150:153]
	global_load_dwordx4 v[178:181], v[176:177], off offset:896
	v_sub_f32_e32 v11, v11, v112
	v_sub_f32_e32 v10, v10, v112
	v_sub_f32_e32 v107, v107, v112
	v_sub_f32_e32 v106, v106, v112
	v_sub_f32_e32 v109, v109, v112
	v_sub_f32_e32 v108, v108, v112
	v_sub_f32_e32 v1, v1, v112
	v_sub_f32_e32 v0, v0, v112
	v_mul_f32_e32 v11, 0x3fb8aa3b, v11
	v_mul_f32_e32 v10, 0x3fb8aa3b, v10
	v_mul_f32_e32 v107, 0x3fb8aa3b, v107
	v_mul_f32_e32 v106, 0x3fb8aa3b, v106
	v_mul_f32_e32 v109, 0x3fb8aa3b, v109
	v_mul_f32_e32 v108, 0x3fb8aa3b, v108
	v_mul_f32_e32 v1, 0x3fb8aa3b, v1
	v_mul_f32_e32 v0, 0x3fb8aa3b, v0
	v_exp_f32_e32 v11, v11
	v_exp_f32_e32 v10, v10
	v_exp_f32_e32 v107, v107
	v_exp_f32_e32 v106, v106
	v_exp_f32_e32 v109, v109
	v_exp_f32_e32 v108, v108
	v_exp_f32_e32 v1, v1
	v_exp_f32_e32 v0, v0
	v_add_f32_e32 v113, v11, v113
	v_add_f32_e32 v113, v10, v113
	v_add_f32_e32 v113, v107, v113
	v_add_f32_e32 v113, v106, v113
	v_add_f32_e32 v113, v109, v113
	v_add_f32_e32 v113, v108, v113
	v_add_f32_e32 v113, v1, v113
	v_add_f32_e32 v113, v0, v113
	v_cvt_pk_bf16_f32 v158, v11, v10
	v_cvt_pk_bf16_f32 v159, v107, v106
	v_cvt_pk_bf16_f32 v160, v109, v108
	v_cvt_pk_bf16_f32 v161, v1, v0
	s_nop 1
	s_waitcnt vmcnt(7)
; __device__ __forceinline__ unsigned pk2(float lo, float hi) { unsigned r; asm("v_cvt_pk_bf16_f32 %0, %1, %2" : "=v"(r) : "v"(lo), "v"(hi)); return r; }
; __device__ void na_phase(const bf16_t* zna  , const bf16_t* vtn  , const float* rpb, bf16_t* ya, int half, unsigned* counter) {
;     ...
;         sm += __shfl_xor(sm, 16); sm += __shfl_xor(sm, 32);
;         f32x4 o[8];
; #pragma unroll
;         for (int dt = 0; dt < 8; ++dt) o[dt] = (f32x4){0.f, 0.f, 0.f, 0.f};
;         const bf16_t* vb = vtn + (size_t)(h * 128 + fr) * TH + (size_t)krow0 * 64 + kstart + fq * 8;
; #pragma unroll
;         for (int a = 0; a < 8; ++a) {
;             const u32x4 pw = (u32x4){pk2(s[2 * a][0], s[2 * a][1]), pk2(s[2 * a][2], s[2 * a][3]), pk2(s[2 * a + 1][0], s[2 * a + 1][1]), pk2(s[2 * a + 1][2], s[2 * a + 1][3])};
;             const bf16x8 pf = *(const bf16x8*)&pw;
; #pragma unroll
;             for (int dt = 0; dt < 8; ++dt) { const bf16x8 vf = *(const bf16x8*)(vb + (size_t)dt * 16 * TH + a * 64);
;                 o[dt] = __builtin_amdgcn_mfma_f32_16x16x32_bf16(vf, pf, o[dt], 0, 0, 0); }
;         }
;         const float inv = 1.0f / sm;
;         bf16_t* op = ya + (size_t)(rowidx * 64 + cbk * 16 + fr) * 1024 + h * 128 + fq * 4;
; #pragma unroll
;         for (int dt = 0; dt < 8; ++dt) { u32x2 w; w.x = pk2(o[dt][0] * inv, o[dt][1] * inv); w.y = pk2(o[dt][2] * inv, o[dt][3] * inv); *(u32x2*)(op + dt * 16) = w; }
	v_mfma_f32_16x16x32_bf16 v[122:125], v[204:207], v[158:161], v[122:125]
	s_waitcnt vmcnt(6)
	v_mfma_f32_16x16x32_bf16 v[126:129], v[208:211], v[158:161], v[126:129]
	s_waitcnt vmcnt(5)
	v_mfma_f32_16x16x32_bf16 v[130:133], v[212:215], v[158:161], v[130:133]
	s_waitcnt vmcnt(4)
	v_mfma_f32_16x16x32_bf16 v[134:137], v[216:219], v[158:161], v[134:137]
	s_waitcnt vmcnt(3)
	v_mfma_f32_16x16x32_bf16 v[138:141], v[220:223], v[158:161], v[138:141]
	s_waitcnt vmcnt(2)
	v_mfma_f32_16x16x32_bf16 v[142:145], v[224:227], v[158:161], v[142:145]
	s_waitcnt vmcnt(1)
	v_mfma_f32_16x16x32_bf16 v[146:149], v[228:231], v[158:161], v[146:149]
	s_waitcnt vmcnt(0)
	v_mfma_f32_16x16x32_bf16 v[150:153], v[178:181], v[158:161], v[150:153]
	ds_bpermute_b32 v114, v110, v113
	s_waitcnt lgkmcnt(0)
	v_add_f32_e32 v113, v113, v114
	ds_bpermute_b32 v114, v111, v113
	s_waitcnt lgkmcnt(0)
	v_add_f32_e32 v113, v113, v114
	v_div_scale_f32 v116, s[10:11], v113, v113, 1.0
	v_readlane_b32 s0, v253, 19
	v_readlane_b32 s1, v253, 20
	v_rcp_f32_e32 v117, v116
	s_nop 0
	v_fma_f32 v118, -v116, v117, 1.0
	v_fmac_f32_e32 v117, v118, v117
	v_div_scale_f32 v118, vcc, 1.0, v113, 1.0
	v_mul_f32_e32 v119, v118, v117
	v_fma_f32 v120, -v116, v119, v118
	v_fmac_f32_e32 v119, v120, v117
	v_fma_f32 v116, -v116, v119, v118
	v_div_fmas_f32 v116, v116, v117, v119
	v_div_fixup_f32 v117, v116, v113, 1.0
	v_lshlrev_b64 v[182:183], 11, v[80:81]
	v_lshl_add_u64 v[182:183], s[0:1], 0, v[182:183]
	v_lshl_add_u64 v[182:183], v[182:183], 0, s[52:53]
	v_lshl_add_u64 v[182:183], v[182:183], 0, v[78:79]
	v_mul_f32_e32 v114, v117, v122
	v_mul_f32_e32 v115, v117, v123
	v_cvt_pk_bf16_f32 v114, v114, v115
	v_mul_f32_e32 v115, v117, v124
	v_mul_f32_e32 v121, v117, v125
	v_cvt_pk_bf16_f32 v115, v115, v121
	global_store_dwordx2 v[182:183], v[114:115], off
	v_mul_f32_e32 v118, v117, v126
	v_mul_f32_e32 v119, v117, v127
	v_cvt_pk_bf16_f32 v118, v118, v119
	v_mul_f32_e32 v119, v117, v128
	v_mul_f32_e32 v121, v117, v129
	v_cvt_pk_bf16_f32 v119, v119, v121
	global_store_dwordx2 v[182:183], v[118:119], off offset:32
	v_mul_f32_e32 v114, v117, v130
	v_mul_f32_e32 v115, v117, v131
	v_cvt_pk_bf16_f32 v114, v114, v115
	v_mul_f32_e32 v115, v117, v132
	v_mul_f32_e32 v121, v117, v133
	v_cvt_pk_bf16_f32 v115, v115, v121
	global_store_dwordx2 v[182:183], v[114:115], off offset:64
	v_mul_f32_e32 v118, v117, v134
	v_mul_f32_e32 v119, v117, v135
	v_cvt_pk_bf16_f32 v118, v118, v119
	v_mul_f32_e32 v119, v117, v136
	v_mul_f32_e32 v121, v117, v137
	v_cvt_pk_bf16_f32 v119, v119, v121
	global_store_dwordx2 v[182:183], v[118:119], off offset:96
	v_mul_f32_e32 v114, v117, v138
	v_mul_f32_e32 v115, v117, v139
	v_cvt_pk_bf16_f32 v114, v114, v115
	v_mul_f32_e32 v115, v117, v140
	v_mul_f32_e32 v121, v117, v141
	v_cvt_pk_bf16_f32 v115, v115, v121
	global_store_dwordx2 v[182:183], v[114:115], off offset:128
	v_mul_f32_e32 v118, v117, v142
	v_mul_f32_e32 v119, v117, v143
	v_cvt_pk_bf16_f32 v118, v118, v119
	v_mul_f32_e32 v119, v117, v144
	v_mul_f32_e32 v121, v117, v145
	v_cvt_pk_bf16_f32 v119, v119, v121
	global_store_dwordx2 v[182:183], v[118:119], off offset:160
	v_mul_f32_e32 v114, v117, v146
	v_mul_f32_e32 v115, v117, v147
	v_cvt_pk_bf16_f32 v114, v114, v115
	v_mul_f32_e32 v115, v117, v148
	v_mul_f32_e32 v121, v117, v149
	v_cvt_pk_bf16_f32 v115, v115, v121
	global_store_dwordx2 v[182:183], v[114:115], off offset:192
	v_mul_f32_e32 v118, v117, v150
	v_mul_f32_e32 v119, v117, v151
	v_cvt_pk_bf16_f32 v118, v118, v119
	v_mul_f32_e32 v119, v117, v152
	v_mul_f32_e32 v121, v117, v153
	v_cvt_pk_bf16_f32 v119, v119, v121
	global_store_dwordx2 v[182:183], v[118:119], off offset:224

; __device__ void na_phase(const bf16_t* zna  , const bf16_t* vtn  , const float* rpb, bf16_t* ya, int half, unsigned* counter) {
;     ...
;         item = __builtin_amdgcn_readfirstlane(item); hq = __builtin_amdgcn_readfirstlane(hq);
;         if (item < 0) break;
;         const int h = item / NPH, rem = item - h * NPH, cbk = rem & 3, rowidx = rem >> 2;
;         int seqrow0, rows;
;         if (half == 0) { if (rowidx < 128) { seqrow0 = 0; rows = 128; } else { seqrow0 = 128 + ((rowidx - 128) >> 6) * 64; rows = 64; } }
;         else { seqrow0 = (rowidx >> 6) * 64; rows = 64; }
;         const int r = rowidx - seqrow0;
;         const int rs = min(max(r - 4, 0), rows - 8);
;         const int kstart = min(max(cbk * 16 - 8, 0), 32);
;         const int krow0 = seqrow0 + rs;
;         bf16x8 qf[4];
;         { const bf16_t* qp = zna + (size_t)(rowidx * 64 + cbk * 16 + fr) * 2048 + h * 128 + fq * 8;
; #pragma unroll
;           for (int kk = 0; kk < 4; ++kk) qf[kk] = *(const bf16x8*)(qp + kk * 32); }
;         f32x4 s[16];
;         const int jperm = 8 * (fr >> 2) + (fr & 3);
; #pragma unroll
;         for (int a = 0; a < 8; ++a)
; #pragma unroll
;             for (int u = 0; u < 2; ++u) {
;                 const bf16_t* kp = zna + (size_t)((krow0 + a) * 64 + kstart + jperm + 4 * u) * 2048 + 1024 + h * 128 + fq * 8;
;                 f32x4 acc = (f32x4){0.f, 0.f, 0.f, 0.f};
; #pragma unroll
;                 for (int kk = 0; kk < 4; ++kk) acc = __builtin_amdgcn_mfma_f32_16x16x32_bf16(*(const bf16x8*)(kp + kk * 32), qf[kk], acc, 0, 0, 0);
;                 s[a * 2 + u] = acc;
.LBB0_188:
	s_or_b64 exec, exec, s[0:1]
	v_readfirstlane_b32 s0, v1
	s_cmp_lt_i32 s0, 0
	v_readfirstlane_b32 s28, v0
	s_cbranch_scc1 .LBB0_317
	s_mul_hi_u32 s1, s0, 0xcccccccd
	s_lshr_b32 s1, s1, 11
	s_mul_i32 s3, s1, 0xfffff600
	s_add_i32 s3, s3, s0
	s_ashr_i32 s9, s3, 2
	s_and_b32 s3, s9, 0x7fffffc0
	s_cmpk_lt_i32 s9, 0x80
	s_cselect_b32 s10, 0, s3
	s_cselect_b32 s11, 0x78, 56
	s_sub_i32 s3, s9, s10
	s_max_i32 s8, s3, 4
	s_lshl_b32 s0, s0, 4
	s_add_i32 s12, s8, -4
	s_and_b32 s8, s0, 48
	s_lshl_b32 s0, s9, 6
	s_or_b32 s0, s0, s8
	s_min_u32 s9, s12, s11
	v_sub_u32_e64 v0, s8, 8 clamp
	v_or_b32_e32 v80, s0, v84
	s_add_i32 s0, s9, s10
	v_min_u32_e32 v79, 32, v0
	s_lshl_b32 s10, s0, 6
	s_waitcnt vmcnt(0)
	v_or_b32_e32 v4, s10, v79
	v_ashrrev_i32_e32 v81, 31, v80
	v_add_u32_e32 v184, v4, v85
	v_lshlrev_b64 v[0:1], 12, v[80:81]
	v_lshlrev_b64 v[4:5], 12, v[184:185]
	v_lshl_add_u64 v[0:1], s[66:67], 0, v[0:1]
	s_lshl_b32 s52, s1, 8
	v_lshl_add_u64 v[4:5], s[66:67], 0, v[4:5]
	v_lshl_add_u64 v[0:1], v[0:1], 0, s[52:53]
	v_lshlrev_b64 v[82:83], 1, v[76:77]
	v_lshl_add_u64 v[4:5], v[4:5], 0, s[52:53]
	v_lshl_add_u64 v[0:1], v[0:1], 0, v[82:83]
	v_lshl_add_u64 v[12:13], v[4:5], 0, v[82:83]
	global_load_dwordx4 v[68:71], v[0:1], off
	global_load_dwordx4 v[64:67], v[0:1], off offset:64
	global_load_dwordx4 v[56:59], v[0:1], off offset:128
	s_nop 0
	global_load_dwordx4 v[0:3], v[0:1], off offset:192
	v_readlane_b32 s12, v254, 22
	v_readlane_b32 s13, v254, 23
	v_readlane_b32 s14, v254, 24
	v_readlane_b32 s15, v254, 25
	v_readlane_b32 s16, v254, 26
	v_readlane_b32 s17, v254, 27
	v_readlane_b32 s18, v254, 28
	v_readlane_b32 s19, v254, 29
	v_readlane_b32 s20, v254, 30
	v_readlane_b32 s21, v254, 31
	v_readlane_b32 s22, v254, 32
	v_readlane_b32 s23, v254, 33
	v_readlane_b32 s24, v254, 34
	v_readlane_b32 s25, v254, 35
	v_readlane_b32 s26, v254, 36
	v_readlane_b32 s27, v254, 37
	s_mov_b64 s[12:13], s[16:17]
	s_mov_b64 s[14:15], s[18:19]
	s_mov_b64 s[16:17], s[20:21]
	s_mov_b64 s[18:19], s[22:23]
	s_mov_b64 s[20:21], s[24:25]
	s_mov_b64 s[22:23], s[26:27]
	v_mov_b32_e32 v224, v12
	v_mov_b32_e32 v225, v13
	v_mov_b32_e32 v226, v224
	v_mov_b32_e32 v227, v225
	global_load_dwordx4 v[122:125], v[226:227], off offset:2048
	global_load_dwordx4 v[126:129], v[226:227], off offset:2112
	global_load_dwordx4 v[130:133], v[226:227], off offset:2176
	global_load_dwordx4 v[134:137], v[226:227], off offset:2240
	v_add_co_u32_e32 v226, vcc, 0x4000, v224
	s_nop 1
	v_addc_co_u32_e32 v227, vcc, 0, v225, vcc
	global_load_dwordx4 v[138:141], v[226:227], off offset:2048
	global_load_dwordx4 v[142:145], v[226:227], off offset:2112
	global_load_dwordx4 v[146:149], v[226:227], off offset:2176
	global_load_dwordx4 v[150:153], v[226:227], off offset:2240
	v_add_co_u32_e32 v226, vcc, 0x40000, v224
	s_nop 1
	v_addc_co_u32_e32 v227, vcc, 0, v225, vcc
	global_load_dwordx4 v[154:157], v[226:227], off offset:2048
	global_load_dwordx4 v[158:161], v[226:227], off offset:2112
	global_load_dwordx4 v[162:165], v[226:227], off offset:2176
	global_load_dwordx4 v[166:169], v[226:227], off offset:2240
	v_add_co_u32_e32 v226, vcc, 0x44000, v224
	s_nop 1
	v_addc_co_u32_e32 v227, vcc, 0, v225, vcc
	global_load_dwordx4 v[170:173], v[226:227], off offset:2048
	global_load_dwordx4 v[174:177], v[226:227], off offset:2112
	global_load_dwordx4 v[178:181], v[226:227], off offset:2176
	global_load_dwordx4 v[204:207], v[226:227], off offset:2240
	v_add_co_u32_e32 v226, vcc, 0x80000, v224
	s_nop 1
	v_addc_co_u32_e32 v227, vcc, 0, v225, vcc
	global_load_dwordx4 v[208:211], v[226:227], off offset:2048
	global_load_dwordx4 v[212:215], v[226:227], off offset:2112
	global_load_dwordx4 v[216:219], v[226:227], off offset:2176
	global_load_dwordx4 v[220:223], v[226:227], off offset:2240
	s_waitcnt vmcnt(19)
	v_mfma_f32_16x16x32_bf16 v[40:43], v[122:125], v[68:71], 0
	v_add_co_u32_e32 v226, vcc, 0x84000, v224
	s_nop 1
	v_addc_co_u32_e32 v227, vcc, 0, v225, vcc
	global_load_dwordx4 v[122:125], v[226:227], off offset:2048
	s_waitcnt vmcnt(19)
	v_mfma_f32_16x16x32_bf16 v[40:43], v[126:129], v[64:67], v[40:43]
	global_load_dwordx4 v[126:129], v[226:227], off offset:2112
	s_waitcnt vmcnt(19)
	v_mfma_f32_16x16x32_bf16 v[40:43], v[130:133], v[56:59], v[40:43]
	global_load_dwordx4 v[130:133], v[226:227], off offset:2176
	s_waitcnt vmcnt(19)
	v_mfma_f32_16x16x32_bf16 v[40:43], v[134:137], v[0:3], v[40:43]
	global_load_dwordx4 v[134:137], v[226:227], off offset:2240
	s_waitcnt vmcnt(19)
	v_mfma_f32_16x16x32_bf16 v[28:31], v[138:141], v[68:71], 0
	v_add_co_u32_e32 v226, vcc, 0xc0000, v224
	s_nop 1
	v_addc_co_u32_e32 v227, vcc, 0, v225, vcc
	global_load_dwordx4 v[138:141], v[226:227], off offset:2048
	s_waitcnt vmcnt(19)
	v_mfma_f32_16x16x32_bf16 v[28:31], v[142:145], v[64:67], v[28:31]
	global_load_dwordx4 v[142:145], v[226:227], off offset:2112
	s_waitcnt vmcnt(19)
	v_mfma_f32_16x16x32_bf16 v[28:31], v[146:149], v[56:59], v[28:31]
	global_load_dwordx4 v[146:149], v[226:227], off offset:2176
	s_waitcnt vmcnt(19)
	v_mfma_f32_16x16x32_bf16 v[28:31], v[150:153], v[0:3], v[28:31]
	global_load_dwordx4 v[150:153], v[226:227], off offset:2240
	s_waitcnt vmcnt(19)
	v_mfma_f32_16x16x32_bf16 v[20:23], v[154:157], v[68:71], 0
	v_add_co_u32_e32 v226, vcc, 0xc4000, v224
	s_nop 1
	v_addc_co_u32_e32 v227, vcc, 0, v225, vcc
	global_load_dwordx4 v[154:157], v[226:227], off offset:2048
	s_waitcnt vmcnt(19)
	v_mfma_f32_16x16x32_bf16 v[20:23], v[158:161], v[64:67], v[20:23]
	global_load_dwordx4 v[158:161], v[226:227], off offset:2112
	s_waitcnt vmcnt(19)
	v_mfma_f32_16x16x32_bf16 v[20:23], v[162:165], v[56:59], v[20:23]
	global_load_dwordx4 v[162:165], v[226:227], off offset:2176
	s_waitcnt vmcnt(19)
; __device__ void na_phase(const bf16_t* zna  , const bf16_t* vtn  , const float* rpb, bf16_t* ya, int half, unsigned* counter) {
;     ...
; #pragma unroll
;         for (int a = 0; a < 8; ++a)
; #pragma unroll
;             for (int u = 0; u < 2; ++u) {
;                 const bf16_t* kp = zna + (size_t)((krow0 + a) * 64 + kstart + jperm + 4 * u) * 2048 + 1024 + h * 128 + fq * 8;
;                 f32x4 acc = (f32x4){0.f, 0.f, 0.f, 0.f};
; #pragma unroll
;                 for (int kk = 0; kk < 4; ++kk) acc = __builtin_amdgcn_mfma_f32_16x16x32_bf16(*(const bf16x8*)(kp + kk * 32), qf[kk], acc, 0, 0, 0);
;                 s[a * 2 + u] = acc;
;             }
	v_mfma_f32_16x16x32_bf16 v[20:23], v[166:169], v[0:3], v[20:23]
	global_load_dwordx4 v[166:169], v[226:227], off offset:2240
	s_waitcnt vmcnt(19)
	v_mfma_f32_16x16x32_bf16 v[16:19], v[170:173], v[68:71], 0
	v_add_co_u32_e32 v226, vcc, 0x100000, v224
	s_nop 1
	v_addc_co_u32_e32 v227, vcc, 0, v225, vcc
	global_load_dwordx4 v[170:173], v[226:227], off offset:2048
	s_waitcnt vmcnt(19)
	v_mfma_f32_16x16x32_bf16 v[16:19], v[174:177], v[64:67], v[16:19]
	global_load_dwordx4 v[174:177], v[226:227], off offset:2112
	s_waitcnt vmcnt(19)
	v_mfma_f32_16x16x32_bf16 v[16:19], v[178:181], v[56:59], v[16:19]
	global_load_dwordx4 v[178:181], v[226:227], off offset:2176
	s_waitcnt vmcnt(19)
	v_mfma_f32_16x16x32_bf16 v[16:19], v[204:207], v[0:3], v[16:19]
	global_load_dwordx4 v[204:207], v[226:227], off offset:2240
	s_waitcnt vmcnt(19)
	v_mfma_f32_16x16x32_bf16 v[12:15], v[208:211], v[68:71], 0
	v_add_co_u32_e32 v226, vcc, 0x104000, v224
	s_nop 1
	v_addc_co_u32_e32 v227, vcc, 0, v225, vcc
	global_load_dwordx4 v[208:211], v[226:227], off offset:2048
	s_waitcnt vmcnt(19)
	v_mfma_f32_16x16x32_bf16 v[12:15], v[212:215], v[64:67], v[12:15]
	global_load_dwordx4 v[212:215], v[226:227], off offset:2112
	s_waitcnt vmcnt(19)
	v_mfma_f32_16x16x32_bf16 v[12:15], v[216:219], v[56:59], v[12:15]
	global_load_dwordx4 v[216:219], v[226:227], off offset:2176
	s_waitcnt vmcnt(19)
	v_mfma_f32_16x16x32_bf16 v[12:15], v[220:223], v[0:3], v[12:15]
	global_load_dwordx4 v[220:223], v[226:227], off offset:2240
	s_waitcnt vmcnt(19)
	v_mfma_f32_16x16x32_bf16 v[72:75], v[122:125], v[68:71], 0
	v_add_co_u32_e32 v226, vcc, 0x140000, v224
	s_nop 1
	v_addc_co_u32_e32 v227, vcc, 0, v225, vcc
	global_load_dwordx4 v[122:125], v[226:227], off offset:2048
	s_waitcnt vmcnt(19)
	v_mfma_f32_16x16x32_bf16 v[72:75], v[126:129], v[64:67], v[72:75]
	global_load_dwordx4 v[126:129], v[226:227], off offset:2112
	s_waitcnt vmcnt(19)
	v_mfma_f32_16x16x32_bf16 v[72:75], v[130:133], v[56:59], v[72:75]
	global_load_dwordx4 v[130:133], v[226:227], off offset:2176
	s_waitcnt vmcnt(19)
	v_mfma_f32_16x16x32_bf16 v[72:75], v[134:137], v[0:3], v[72:75]
	global_load_dwordx4 v[134:137], v[226:227], off offset:2240
	s_waitcnt vmcnt(19)
	v_mfma_f32_16x16x32_bf16 v[60:63], v[138:141], v[68:71], 0
	v_add_co_u32_e32 v226, vcc, 0x144000, v224
	s_nop 1
	v_addc_co_u32_e32 v227, vcc, 0, v225, vcc
	global_load_dwordx4 v[138:141], v[226:227], off offset:2048
	s_waitcnt vmcnt(19)
	v_mfma_f32_16x16x32_bf16 v[60:63], v[142:145], v[64:67], v[60:63]
	global_load_dwordx4 v[142:145], v[226:227], off offset:2112
	s_waitcnt vmcnt(19)
	v_mfma_f32_16x16x32_bf16 v[60:63], v[146:149], v[56:59], v[60:63]
	global_load_dwordx4 v[146:149], v[226:227], off offset:2176
	s_waitcnt vmcnt(19)
	v_mfma_f32_16x16x32_bf16 v[60:63], v[150:153], v[0:3], v[60:63]
	global_load_dwordx4 v[150:153], v[226:227], off offset:2240
	s_waitcnt vmcnt(19)
	v_mfma_f32_16x16x32_bf16 v[52:55], v[154:157], v[68:71], 0
	v_add_co_u32_e32 v226, vcc, 0x180000, v224
	s_nop 1
	v_addc_co_u32_e32 v227, vcc, 0, v225, vcc
	global_load_dwordx4 v[154:157], v[226:227], off offset:2048
	s_waitcnt vmcnt(19)
	v_mfma_f32_16x16x32_bf16 v[52:55], v[158:161], v[64:67], v[52:55]
	global_load_dwordx4 v[158:161], v[226:227], off offset:2112
	s_waitcnt vmcnt(19)
	v_mfma_f32_16x16x32_bf16 v[52:55], v[162:165], v[56:59], v[52:55]
	global_load_dwordx4 v[162:165], v[226:227], off offset:2176
	s_waitcnt vmcnt(19)
	v_mfma_f32_16x16x32_bf16 v[52:55], v[166:169], v[0:3], v[52:55]
	global_load_dwordx4 v[166:169], v[226:227], off offset:2240
	s_waitcnt vmcnt(19)
	v_mfma_f32_16x16x32_bf16 v[48:51], v[170:173], v[68:71], 0
	v_add_co_u32_e32 v226, vcc, 0x184000, v224
	s_nop 1
	v_addc_co_u32_e32 v227, vcc, 0, v225, vcc
	global_load_dwordx4 v[170:173], v[226:227], off offset:2048
	s_waitcnt vmcnt(19)
	v_mfma_f32_16x16x32_bf16 v[48:51], v[174:177], v[64:67], v[48:51]
	global_load_dwordx4 v[174:177], v[226:227], off offset:2112
	s_waitcnt vmcnt(19)
	v_mfma_f32_16x16x32_bf16 v[48:51], v[178:181], v[56:59], v[48:51]
	global_load_dwordx4 v[178:181], v[226:227], off offset:2176
	s_waitcnt vmcnt(19)
	v_mfma_f32_16x16x32_bf16 v[48:51], v[204:207], v[0:3], v[48:51]
	global_load_dwordx4 v[204:207], v[226:227], off offset:2240
	s_waitcnt vmcnt(19)
	v_mfma_f32_16x16x32_bf16 v[44:47], v[208:211], v[68:71], 0
	v_add_co_u32_e32 v226, vcc, 0x1c0000, v224
	s_nop 1
	v_addc_co_u32_e32 v227, vcc, 0, v225, vcc
	global_load_dwordx4 v[208:211], v[226:227], off offset:2048
	s_waitcnt vmcnt(19)
	v_mfma_f32_16x16x32_bf16 v[44:47], v[212:215], v[64:67], v[44:47]
	global_load_dwordx4 v[212:215], v[226:227], off offset:2112
	s_waitcnt vmcnt(19)
	v_mfma_f32_16x16x32_bf16 v[44:47], v[216:219], v[56:59], v[44:47]
	global_load_dwordx4 v[216:219], v[226:227], off offset:2176
	s_waitcnt vmcnt(19)
	v_mfma_f32_16x16x32_bf16 v[44:47], v[220:223], v[0:3], v[44:47]
	global_load_dwordx4 v[220:223], v[226:227], off offset:2240
	s_waitcnt vmcnt(19)
	v_mfma_f32_16x16x32_bf16 v[36:39], v[122:125], v[68:71], 0
	v_add_co_u32_e32 v226, vcc, 0x1c4000, v224
	s_nop 1
	v_addc_co_u32_e32 v227, vcc, 0, v225, vcc
	global_load_dwordx4 v[122:125], v[226:227], off offset:2048
	s_waitcnt vmcnt(19)
	v_mfma_f32_16x16x32_bf16 v[36:39], v[126:129], v[64:67], v[36:39]
	global_load_dwordx4 v[126:129], v[226:227], off offset:2112
	s_waitcnt vmcnt(19)
	v_mfma_f32_16x16x32_bf16 v[36:39], v[130:133], v[56:59], v[36:39]
	global_load_dwordx4 v[130:133], v[226:227], off offset:2176
	s_waitcnt vmcnt(19)
	v_mfma_f32_16x16x32_bf16 v[36:39], v[134:137], v[0:3], v[36:39]
	global_load_dwordx4 v[134:137], v[226:227], off offset:2240
	s_waitcnt vmcnt(19)
; __device__ void na_phase(const bf16_t* zna  , const bf16_t* vtn  , const float* rpb, bf16_t* ya, int half, unsigned* counter) {
;     ...
;         for (int a = 0; a < 8; ++a)
; #pragma unroll
;             for (int u = 0; u < 2; ++u) {
;                 const bf16_t* kp = zna + (size_t)((krow0 + a) * 64 + kstart + jperm + 4 * u) * 2048 + 1024 + h * 128 + fq * 8;
;                 f32x4 acc = (f32x4){0.f, 0.f, 0.f, 0.f};
; #pragma unroll
;                 for (int kk = 0; kk < 4; ++kk) acc = __builtin_amdgcn_mfma_f32_16x16x32_bf16(*(const bf16x8*)(kp + kk * 32), qf[kk], acc, 0, 0, 0);
;                 s[a * 2 + u] = acc;
;             }
;         const int c = cbk * 16 + fr, wsx = min(max(c - 8, 0), 48);
;         const float* bp = rpb + (h * 15 + (rs - r + 7)) * 31;
;         float mx = -INFINITY;
; #pragma unroll
;         for (int a = 0; a < 8; ++a)
; #pragma unroll
;             for (int u = 0; u < 2; ++u)
; #pragma unroll
;                 for (int j = 0; j < 4; ++j) { const int kc = kstart + 8 * fq + 4 * u + j; const bool valid = (kc >= wsx) && (kc < wsx + 16);
;                     const int ci = min(max(kc - c + 15, 0), 30);
;                     const float v = valid ? s[a * 2 + u][j] * 0.08838834764831845f + bp[a * 31 + ci] : -INFINITY;
	v_mfma_f32_16x16x32_bf16 v[32:35], v[138:141], v[68:71], 0
	s_waitcnt vmcnt(18)
	v_mfma_f32_16x16x32_bf16 v[32:35], v[142:145], v[64:67], v[32:35]
	s_waitcnt vmcnt(17)
	v_mfma_f32_16x16x32_bf16 v[32:35], v[146:149], v[56:59], v[32:35]
	s_waitcnt vmcnt(16)
	v_mfma_f32_16x16x32_bf16 v[32:35], v[150:153], v[0:3], v[32:35]
	s_waitcnt vmcnt(15)
	v_mfma_f32_16x16x32_bf16 v[24:27], v[154:157], v[68:71], 0
	s_waitcnt vmcnt(14)
	v_mfma_f32_16x16x32_bf16 v[24:27], v[158:161], v[64:67], v[24:27]
	s_waitcnt vmcnt(13)
	v_mfma_f32_16x16x32_bf16 v[24:27], v[162:165], v[56:59], v[24:27]
	s_waitcnt vmcnt(12)
	v_mfma_f32_16x16x32_bf16 v[24:27], v[166:169], v[0:3], v[24:27]
	s_waitcnt vmcnt(11)
	v_mfma_f32_16x16x32_bf16 v[8:11], v[170:173], v[68:71], 0
	s_waitcnt vmcnt(10)
	v_mfma_f32_16x16x32_bf16 v[8:11], v[174:177], v[64:67], v[8:11]
	s_waitcnt vmcnt(9)
	v_mfma_f32_16x16x32_bf16 v[8:11], v[178:181], v[56:59], v[8:11]
	s_waitcnt vmcnt(8)
	v_mfma_f32_16x16x32_bf16 v[8:11], v[204:207], v[0:3], v[8:11]
	s_waitcnt vmcnt(7)
	v_mfma_f32_16x16x32_bf16 v[4:7], v[208:211], v[68:71], 0
	s_waitcnt vmcnt(6)
	v_mfma_f32_16x16x32_bf16 v[4:7], v[212:215], v[64:67], v[4:7]
	s_waitcnt vmcnt(5)
	v_mfma_f32_16x16x32_bf16 v[4:7], v[216:219], v[56:59], v[4:7]
	s_waitcnt vmcnt(4)
	v_mfma_f32_16x16x32_bf16 v[4:7], v[220:223], v[0:3], v[4:7]
	s_waitcnt vmcnt(3)
	v_mfma_f32_16x16x32_bf16 v[228:231], v[122:125], v[68:71], 0
	s_waitcnt vmcnt(2)
	v_mfma_f32_16x16x32_bf16 v[228:231], v[126:129], v[64:67], v[228:231]
	s_waitcnt vmcnt(1)
	v_mfma_f32_16x16x32_bf16 v[228:231], v[130:133], v[56:59], v[228:231]
	s_waitcnt vmcnt(0)
	v_mfma_f32_16x16x32_bf16 v[0:3], v[134:137], v[0:3], v[228:231]
	v_add_u32_e32 v184, 0x1c4, v184
	v_add_u32_e32 v82, v79, v76
	v_or_b32_e32 v64, s8, v84
	s_mul_i32 s8, s1, 15
	s_sub_i32 s3, s8, s3
	s_add_i32 s3, s3, s9
	s_mul_i32 s3, s3, 31
	v_max_i32_e32 v56, 8, v64
	s_add_i32 s8, s3, 0xd9
	v_add_u32_e32 v56, -8, v56
	s_ashr_i32 s9, s8, 31
	v_min_u32_e32 v70, 48, v56
	s_lshl_b64 s[8:9], s[8:9], 2
	s_add_u32 s10, s22, s8
	v_add_u32_e32 v71, 16, v70
	s_addc_u32 s11, s23, s9
	v_mov_b32_e32 v216, 0xff800000
	v_mov_b32_e32 v217, 0x3db504f3
	v_cmp_ge_u32_e32 vcc, v82, v70
	v_cmp_lt_u32_e64 s[8:9], v82, v71
	v_sub_u32_e32 v215, v82, v64
	s_and_b64 s[12:13], vcc, s[8:9]
	v_max_i32_e32 v215, -15, v215
	v_add_u32_e32 v215, 15, v215
	v_min_u32_e32 v215, 30, v215
	v_lshlrev_b32_e32 v206, 2, v215
	v_or_b32_e32 v214, 1, v82
	v_cmp_ge_u32_e32 vcc, v214, v70
	v_cmp_lt_u32_e64 s[8:9], v214, v71
	v_sub_u32_e32 v215, v214, v64
	s_and_b64 s[14:15], vcc, s[8:9]
	v_max_i32_e32 v215, -15, v215
	v_add_u32_e32 v215, 15, v215
	v_min_u32_e32 v215, 30, v215
	v_lshlrev_b32_e32 v207, 2, v215
	v_or_b32_e32 v214, 2, v82
	v_cmp_ge_u32_e32 vcc, v214, v70
	v_cmp_lt_u32_e64 s[8:9], v214, v71
	v_sub_u32_e32 v215, v214, v64
	s_and_b64 s[16:17], vcc, s[8:9]
	v_max_i32_e32 v215, -15, v215
	v_add_u32_e32 v215, 15, v215
	v_min_u32_e32 v215, 30, v215
	v_lshlrev_b32_e32 v208, 2, v215
	v_or_b32_e32 v214, 3, v82
	v_cmp_ge_u32_e32 vcc, v214, v70
	v_cmp_lt_u32_e64 s[8:9], v214, v71
	v_sub_u32_e32 v215, v214, v64
	s_and_b64 s[18:19], vcc, s[8:9]
	v_max_i32_e32 v215, -15, v215
	v_add_u32_e32 v215, 15, v215
	v_min_u32_e32 v215, 30, v215
	v_lshlrev_b32_e32 v209, 2, v215
	v_or_b32_e32 v214, 4, v82
	v_cmp_ge_u32_e32 vcc, v214, v70
	v_cmp_lt_u32_e64 s[8:9], v214, v71
	v_sub_u32_e32 v215, v214, v64
	s_and_b64 s[20:21], vcc, s[8:9]
	v_max_i32_e32 v215, -15, v215
	v_add_u32_e32 v215, 15, v215
	v_min_u32_e32 v215, 30, v215
	v_lshlrev_b32_e32 v210, 2, v215
	v_or_b32_e32 v214, 5, v82
	v_cmp_ge_u32_e32 vcc, v214, v70
	v_cmp_lt_u32_e64 s[8:9], v214, v71
	v_sub_u32_e32 v215, v214, v64
	s_and_b64 s[22:23], vcc, s[8:9]
	v_max_i32_e32 v215, -15, v215
	v_add_u32_e32 v215, 15, v215
	v_min_u32_e32 v215, 30, v215
	v_lshlrev_b32_e32 v211, 2, v215
	v_or_b32_e32 v214, 6, v82
	v_cmp_ge_u32_e32 vcc, v214, v70
	v_cmp_lt_u32_e64 s[8:9], v214, v71
	v_sub_u32_e32 v215, v214, v64
	s_and_b64 s[24:25], vcc, s[8:9]
	v_max_i32_e32 v215, -15, v215
	v_add_u32_e32 v215, 15, v215
	v_min_u32_e32 v215, 30, v215
	v_lshlrev_b32_e32 v212, 2, v215
	v_or_b32_e32 v214, 7, v82
	v_cmp_ge_u32_e32 vcc, v214, v70
	v_cmp_lt_u32_e64 s[8:9], v214, v71
	v_sub_u32_e32 v215, v214, v64
	s_and_b64 s[26:27], vcc, s[8:9]
	v_max_i32_e32 v215, -15, v215
	v_add_u32_e32 v215, 15, v215
	v_min_u32_e32 v215, 30, v215
	v_lshlrev_b32_e32 v213, 2, v215
	global_load_dword v122, v206, s[10:11]
	global_load_dword v123, v207, s[10:11]
	global_load_dword v124, v208, s[10:11]
	global_load_dword v125, v209, s[10:11]
	global_load_dword v126, v210, s[10:11]
	global_load_dword v127, v211, s[10:11]
	global_load_dword v128, v212, s[10:11]
	global_load_dword v129, v213, s[10:11]
	global_load_dword v130, v206, s[10:11] offset:124
	global_load_dword v131, v207, s[10:11] offset:124
	global_load_dword v132, v208, s[10:11] offset:124
	global_load_dword v133, v209, s[10:11] offset:124
	global_load_dword v134, v210, s[10:11] offset:124
	global_load_dword v135, v211, s[10:11] offset:124
	global_load_dword v136, v212, s[10:11] offset:124
	global_load_dword v137, v213, s[10:11] offset:124
	global_load_dword v138, v206, s[10:11] offset:248
	global_load_dword v139, v207, s[10:11] offset:248
	global_load_dword v140, v208, s[10:11] offset:248
	global_load_dword v141, v209, s[10:11] offset:248
	global_load_dword v142, v210, s[10:11] offset:248
	global_load_dword v143, v211, s[10:11] offset:248
	global_load_dword v144, v212, s[10:11] offset:248
	global_load_dword v145, v213, s[10:11] offset:248
	global_load_dword v146, v206, s[10:11] offset:372
	global_load_dword v147, v207, s[10:11] offset:372
; __device__ void na_phase(const bf16_t* zna  , const bf16_t* vtn  , const float* rpb, bf16_t* ya, int half, unsigned* counter) {
;     ...
;         const int c = cbk * 16 + fr, wsx = min(max(c - 8, 0), 48);
;         const float* bp = rpb + (h * 15 + (rs - r + 7)) * 31;
;         float mx = -INFINITY;
; #pragma unroll
;         for (int a = 0; a < 8; ++a)
; #pragma unroll
;             for (int u = 0; u < 2; ++u)
; #pragma unroll
;                 for (int j = 0; j < 4; ++j) { const int kc = kstart + 8 * fq + 4 * u + j; const bool valid = (kc >= wsx) && (kc < wsx + 16);
;                     const int ci = min(max(kc - c + 15, 0), 30);
;                     const float v = valid ? s[a * 2 + u][j] * 0.08838834764831845f + bp[a * 31 + ci] : -INFINITY;
;                     s[a * 2 + u][j] = v; mx = fmaxf(mx, v); }
	global_load_dword v148, v208, s[10:11] offset:372
	global_load_dword v149, v209, s[10:11] offset:372
	global_load_dword v150, v210, s[10:11] offset:372
	global_load_dword v151, v211, s[10:11] offset:372
	global_load_dword v152, v212, s[10:11] offset:372
	global_load_dword v153, v213, s[10:11] offset:372
	global_load_dword v154, v206, s[10:11] offset:496
	global_load_dword v155, v207, s[10:11] offset:496
	global_load_dword v156, v208, s[10:11] offset:496
	global_load_dword v157, v209, s[10:11] offset:496
	global_load_dword v158, v210, s[10:11] offset:496
	global_load_dword v159, v211, s[10:11] offset:496
	global_load_dword v160, v212, s[10:11] offset:496
	global_load_dword v161, v213, s[10:11] offset:496
	global_load_dword v162, v206, s[10:11] offset:620
	global_load_dword v163, v207, s[10:11] offset:620
	global_load_dword v164, v208, s[10:11] offset:620
	global_load_dword v165, v209, s[10:11] offset:620
	global_load_dword v166, v210, s[10:11] offset:620
	global_load_dword v167, v211, s[10:11] offset:620
	global_load_dword v168, v212, s[10:11] offset:620
	global_load_dword v169, v213, s[10:11] offset:620
	global_load_dword v170, v206, s[10:11] offset:744
	global_load_dword v171, v207, s[10:11] offset:744
	global_load_dword v172, v208, s[10:11] offset:744
	global_load_dword v173, v209, s[10:11] offset:744
	global_load_dword v174, v210, s[10:11] offset:744
	global_load_dword v175, v211, s[10:11] offset:744
	global_load_dword v176, v212, s[10:11] offset:744
	global_load_dword v177, v213, s[10:11] offset:744
	global_load_dword v178, v206, s[10:11] offset:868
	global_load_dword v179, v207, s[10:11] offset:868
	global_load_dword v180, v208, s[10:11] offset:868
	global_load_dword v181, v209, s[10:11] offset:868
	global_load_dword v182, v210, s[10:11] offset:868
	global_load_dword v183, v211, s[10:11] offset:868
	global_load_dword v204, v212, s[10:11] offset:868
	global_load_dword v205, v213, s[10:11] offset:868
	s_waitcnt vmcnt(56)
	v_fma_f32 v57, v217, v40, v122
	v_cndmask_b32_e64 v57, v216, v57, s[12:13]
	v_fma_f32 v56, v217, v41, v123
	v_cndmask_b32_e64 v56, v216, v56, s[14:15]
	v_fma_f32 v41, v217, v42, v124
	v_cndmask_b32_e64 v41, v216, v41, s[16:17]
	v_fma_f32 v40, v217, v43, v125
	v_cndmask_b32_e64 v40, v216, v40, s[18:19]
	v_fma_f32 v43, v217, v28, v126
	v_cndmask_b32_e64 v43, v216, v43, s[20:21]
	v_fma_f32 v42, v217, v29, v127
	v_cndmask_b32_e64 v42, v216, v42, s[22:23]
	v_fma_f32 v29, v217, v30, v128
	v_cndmask_b32_e64 v29, v216, v29, s[24:25]
	v_fma_f32 v28, v217, v31, v129
	v_cndmask_b32_e64 v28, v216, v28, s[26:27]
	s_waitcnt vmcnt(48)
	v_fma_f32 v31, v217, v20, v130
	v_cndmask_b32_e64 v31, v216, v31, s[12:13]
	v_fma_f32 v30, v217, v21, v131
	v_cndmask_b32_e64 v30, v216, v30, s[14:15]
	v_fma_f32 v21, v217, v22, v132
	v_cndmask_b32_e64 v21, v216, v21, s[16:17]
	v_fma_f32 v20, v217, v23, v133
	v_cndmask_b32_e64 v20, v216, v20, s[18:19]
	v_fma_f32 v23, v217, v16, v134
	v_cndmask_b32_e64 v23, v216, v23, s[20:21]
	v_fma_f32 v22, v217, v17, v135
	v_cndmask_b32_e64 v22, v216, v22, s[22:23]
	v_fma_f32 v17, v217, v18, v136
	v_cndmask_b32_e64 v17, v216, v17, s[24:25]
	v_fma_f32 v16, v217, v19, v137
	v_cndmask_b32_e64 v16, v216, v16, s[26:27]
	s_waitcnt vmcnt(40)
	v_fma_f32 v19, v217, v12, v138
	v_cndmask_b32_e64 v19, v216, v19, s[12:13]
	v_fma_f32 v18, v217, v13, v139
	v_cndmask_b32_e64 v18, v216, v18, s[14:15]
	v_fma_f32 v64, v217, v14, v140
	v_cndmask_b32_e64 v64, v216, v64, s[16:17]
	v_fma_f32 v12, v217, v15, v141
	v_cndmask_b32_e64 v12, v216, v12, s[18:19]
	v_fma_f32 v15, v217, v72, v142
	v_cndmask_b32_e64 v15, v216, v15, s[20:21]
	v_fma_f32 v14, v217, v73, v143
	v_cndmask_b32_e64 v14, v216, v14, s[22:23]
	v_fma_f32 v83, v217, v74, v144
	v_cndmask_b32_e64 v83, v216, v83, s[24:25]
	v_fma_f32 v82, v217, v75, v145
	v_cndmask_b32_e64 v82, v216, v82, s[26:27]
	s_waitcnt vmcnt(32)
	v_fma_f32 v75, v217, v60, v146
	v_cndmask_b32_e64 v75, v216, v75, s[12:13]
	v_fma_f32 v74, v217, v61, v147
	v_cndmask_b32_e64 v74, v216, v74, s[14:15]
	v_fma_f32 v87, v217, v62, v148
	v_cndmask_b32_e64 v87, v216, v87, s[16:17]
	v_fma_f32 v86, v217, v63, v149
	v_cndmask_b32_e64 v86, v216, v86, s[18:19]
	v_fma_f32 v89, v217, v52, v150
	v_cndmask_b32_e64 v89, v216, v89, s[20:21]
	v_fma_f32 v88, v217, v53, v151
	v_cndmask_b32_e64 v88, v216, v88, s[22:23]
	v_fma_f32 v91, v217, v54, v152
	v_cndmask_b32_e64 v91, v216, v91, s[24:25]
	v_fma_f32 v90, v217, v55, v153
	v_cndmask_b32_e64 v90, v216, v90, s[26:27]
	s_waitcnt vmcnt(24)
	v_fma_f32 v93, v217, v48, v154
	v_cndmask_b32_e64 v93, v216, v93, s[12:13]
	v_fma_f32 v92, v217, v49, v155
	v_cndmask_b32_e64 v92, v216, v92, s[14:15]
	v_fma_f32 v49, v217, v50, v156
	v_cndmask_b32_e64 v49, v216, v49, s[16:17]
	v_fma_f32 v48, v217, v51, v157
	v_cndmask_b32_e64 v48, v216, v48, s[18:19]
	v_fma_f32 v95, v217, v44, v158
	v_cndmask_b32_e64 v95, v216, v95, s[20:21]
	v_fma_f32 v94, v217, v45, v159
	v_cndmask_b32_e64 v94, v216, v94, s[22:23]
	v_fma_f32 v97, v217, v46, v160
	v_cndmask_b32_e64 v97, v216, v97, s[24:25]
	v_fma_f32 v96, v217, v47, v161
	v_cndmask_b32_e64 v96, v216, v96, s[26:27]
	s_waitcnt vmcnt(16)
	v_fma_f32 v99, v217, v36, v162
	v_cndmask_b32_e64 v99, v216, v99, s[12:13]
	v_fma_f32 v98, v217, v37, v163
	v_cndmask_b32_e64 v98, v216, v98, s[14:15]
	v_fma_f32 v36, v217, v38, v164
	v_cndmask_b32_e64 v36, v216, v36, s[16:17]
	v_fma_f32 v37, v217, v39, v165
	v_cndmask_b32_e64 v37, v216, v37, s[18:19]
	v_fma_f32 v38, v217, v32, v166
	v_cndmask_b32_e64 v38, v216, v38, s[20:21]
	v_fma_f32 v39, v217, v33, v167
	v_cndmask_b32_e64 v39, v216, v39, s[22:23]
	v_fma_f32 v33, v217, v34, v168
	v_cndmask_b32_e64 v33, v216, v33, s[24:25]
	v_fma_f32 v32, v217, v35, v169
	v_cndmask_b32_e64 v32, v216, v32, s[26:27]
	s_waitcnt vmcnt(8)
	v_fma_f32 v101, v217, v24, v170
	v_cndmask_b32_e64 v101, v216, v101, s[12:13]
	v_fma_f32 v100, v217, v25, v171
	v_cndmask_b32_e64 v100, v216, v100, s[14:15]
	v_fma_f32 v103, v217, v26, v172
	v_cndmask_b32_e64 v103, v216, v103, s[16:17]
	v_fma_f32 v102, v217, v27, v173
	v_cndmask_b32_e64 v102, v216, v102, s[18:19]
	v_fma_f32 v26, v217, v8, v174
	v_cndmask_b32_e64 v26, v216, v26, s[20:21]
	v_fma_f32 v27, v217, v9, v175
	v_cndmask_b32_e64 v27, v216, v27, s[22:23]
	v_fma_f32 v105, v217, v10, v176
	v_cndmask_b32_e64 v105, v216, v105, s[24:25]
	v_fma_f32 v104, v217, v11, v177
	v_cndmask_b32_e64 v104, v216, v104, s[26:27]
	s_waitcnt vmcnt(0)
	v_fma_f32 v11, v217, v4, v178
	v_cndmask_b32_e64 v11, v216, v11, s[12:13]
	v_fma_f32 v10, v217, v5, v179
	v_cndmask_b32_e64 v10, v216, v10, s[14:15]
	v_fma_f32 v107, v217, v6, v180
	v_cndmask_b32_e64 v107, v216, v107, s[16:17]
	v_fma_f32 v106, v217, v7, v181
	v_cndmask_b32_e64 v106, v216, v106, s[18:19]
	v_fma_f32 v109, v217, v0, v182
	v_cndmask_b32_e64 v109, v216, v109, s[20:21]
	v_fma_f32 v108, v217, v1, v183
	v_cndmask_b32_e64 v108, v216, v108, s[22:23]
	v_fma_f32 v1, v217, v2, v204
	v_cndmask_b32_e64 v1, v216, v1, s[24:25]
	v_fma_f32 v0, v217, v3, v205
	v_cndmask_b32_e64 v0, v216, v0, s[26:27]
	s_branch .LBB0_179
